# P0 tail loops (RSS zero, w_pw to bf16, state_conv copy) run only on the weight-converting CUs so the x-converting CUs go straight to the barrier
# speedup vs baseline: 1.0602x; 1.0005x over previous
; __global__ void __launch_bounds__(NWAVES * 64, 2) fwd_mega(Args args) {
;     ...
;         const int gt = blockIdx.x * (NWAVES * 64) + tid, NGT = G * NWAVES * 64;
;         for (int i = gt; i < 3 * MT; i += NGT) RSS[MT + i] = 0.f;
.LBB0_60:
	s_lshl_b32 s82, s33, 3
	v_lshl_add_u32 v0, s76, 9, v74
	s_mov_b32 s4, 0xc600
	s_lshl_b32 s12, s33, 9
	s_mov_b32 s77, s95
	s_cmpk_lt_u32 s82, 0x700
	s_cbranch_scc1 .Lt_orig
	s_cmpk_gt_u32 s76, 0x6f
	s_cbranch_scc1 .Lt_skip
	s_mov_b32 s12, 0xe000
.Lt_orig:
	v_cmp_gt_i32_e32 vcc, s4, v0
	s_and_saveexec_b64 s[14:15], vcc
	s_cbranch_execz .LBB0_68
	v_cvt_f32_u32_e32 v2, s12
	v_add_u32_e32 v1, s12, v0
	v_mov_b32_e32 v3, s12
	v_cmp_gt_i32_e32 vcc, s4, v1
	v_rcp_iflag_f32_e32 v2, v2
	s_sub_i32 s13, 0, s12
	v_max_i32_e32 v4, 0xc600, v1
	v_addc_co_u32_e64 v3, s[4:5], v0, v3, vcc
	v_mul_f32_e32 v2, 0x4f7ffffe, v2
	v_cvt_u32_f32_e32 v2, v2
	v_sub_u32_e32 v3, v4, v3
	v_mul_lo_u32 v4, s13, v2
	v_mul_hi_u32 v4, v2, v4
	v_add_u32_e32 v2, v2, v4
	v_mul_hi_u32 v2, v3, v2
	v_mul_lo_u32 v4, v2, s12
	v_sub_u32_e32 v3, v3, v4
	v_add_u32_e32 v5, 1, v2
	v_cmp_le_u32_e64 s[4:5], s12, v3
	v_subrev_u32_e32 v4, s12, v3
	s_nop 0
	v_cndmask_b32_e64 v2, v2, v5, s[4:5]
	v_cndmask_b32_e64 v3, v3, v4, s[4:5]
	v_add_u32_e32 v4, 1, v2
	v_cmp_le_u32_e64 s[4:5], s12, v3
	s_nop 1
	v_cndmask_b32_e64 v2, v2, v4, s[4:5]
	v_addc_co_u32_e32 v4, vcc, 1, v2, vcc
	v_cmp_lt_u32_e32 vcc, 1, v4
	s_mov_b64 s[4:5], -1
	v_mov_b32_e32 v2, v0
	s_and_saveexec_b64 s[16:17], vcc
	s_cbranch_execz .LBB0_65
	v_and_b32_e32 v5, -2, v4
	s_lshl_b32 s13, s12, 1
	s_mov_b32 s20, s13
	s_mov_b64 s[18:19], 0
	v_mov_b32_e32 v6, 0
	v_mov_b32_e32 v7, v5
	v_mov_b64_e32 v[2:3], v[0:1]

; __device__ __forceinline__ unsigned pk2(float lo, float hi) { f32x2 v = {lo, hi}; bf16x2_t b = __builtin_convertvector(v, bf16x2_t); return __builtin_bit_cast(unsigned, b); }
; #define KIN(i) ((const float*)kptr<float>(i))
; __global__ void __launch_bounds__(NWAVES * 64, 2) fwd_mega(Args args) {
;     ...
;         { const float* w_pw = KIN(11);
;           for (int i = gt; i < DEPTH * CCH * (CCH / 8); i += NGT) { const int c8 = i & 63, k = (i >> 6) & 511, ll = i >> 15;
;             const float* sp = w_pw + ((size_t)(ll * CCH + k) * CCH + c8 * 8); const f32x4 a = *(const f32x4*)sp, b = *(const f32x4*)(sp + 4);
;             u32x4 w; w.x = pk2(a[0], a[1]); w.y = pk2(a[2], a[3]); w.z = pk2(b[0], b[1]); w.w = pk2(b[2], b[3]);
;             *(u32x4*)((bf16_t*)(ws + WS_W + (size_t)ll * W_LAYER + W_PWP) + ((size_t)k * DM + c8 * 8)) = w; } }
.LBB0_68:
	s_or_b64 exec, exec, s[14:15]
	s_load_dwordx2 s[2:3], s[0:1], 0x58
	s_mov_b32 s4, 0x10000
	v_cmp_gt_i32_e32 vcc, s4, v0
	s_and_saveexec_b64 s[4:5], vcc
	s_load_dwordx2 s[78:79], s[0:1], 0xa0
	s_cbranch_execz .LBB0_71
	v_lshlrev_b32_e32 v1, 3, v74
	v_lshl_add_u32 v1, s76, 12, v1
	s_lshl_b32 s13, s12, 3
	s_mov_b64 s[14:15], 0
	v_mov_b32_e32 v3, 0
	s_mov_b32 s16, 0x1a00000
	v_mov_b64_e32 v[4:5], s[10:11]
	s_mov_b32 s17, 0xffff
	v_mov_b32_e32 v6, v0

; #define KIN(i) ((const float*)kptr<float>(i))
; __global__ void __launch_bounds__(NWAVES * 64, 2) fwd_mega(Args args) {
;     ...
;         const float* state_conv = KIN(4);
;         for (int i = gt; i < DEPTH * 8 * 30 * (CCH / 4); i += NGT) { const int c4 = i & 127, rr = (i >> 7) % 30, lb = (i >> 7) / 30;
;             *(f32x4*)((float*)(ws + WS_US) + ((size_t)(lb * 94 + rr) * CCH + c4 * 4)) = *(const f32x4*)(state_conv + ((size_t)(lb * 30 + rr) * CCH + c4 * 4)); }
.LBB0_71:
	s_or_b64 exec, exec, s[4:5]
	s_waitcnt lgkmcnt(0)
	s_load_dwordx2 s[2:3], s[0:1], 0x20
	s_mov_b32 s4, 0xf000
	s_mov_b64 s[80:81], s[96:97]
	s_mov_b32 s77, s95
	v_cmp_gt_i32_e32 vcc, s4, v0
	s_and_saveexec_b64 s[4:5], vcc
	s_cbranch_execz .LBB0_74
	s_add_u32 s10, s10, 0x5600000
	v_lshlrev_b32_e32 v1, 2, v74
	s_addc_u32 s11, s11, 0
	v_lshl_add_u32 v1, s76, 11, v1
	s_lshl_b32 s13, s12, 2
	s_mov_b64 s[14:15], 0
	s_mov_b32 s16, 0x88888889
	v_mov_b32_e32 v3, 0
	s_mov_b32 s17, 0xefff

; __device__ __forceinline__ unsigned xb_ld(unsigned* p)              { return __hip_atomic_load(p, __ATOMIC_RELAXED, __HIP_MEMORY_SCOPE_AGENT); }
; __device__ __forceinline__ void xcd_barrier_complete(unsigned* bar, unsigned x, unsigned& nloc, unsigned& nx) {
;     const unsigned G = gridDim.x * gridDim.y * gridDim.z;
;     unsigned sum, cnt, mine, sp = 0u;
;     for (;;) {
;         sum = 0u; cnt = 0u; mine = 0u;
; #pragma unroll
;         for (unsigned j = 0; j < 16; ++j) { const unsigned c = xb_ld(&bar[XB_XCNT(j)]); sum += c; cnt += (c > 0u) ? 1u : 0u; mine = (j == x) ? c : mine; }
;         if (sum == G) break;
; __device__ __forceinline__ void xcd_barrier(const XcdBarrier& b) {
;     asm volatile("s_waitcnt vmcnt(0)" ::: "memory");
;     __syncthreads();
;     if (threadIdx.x == 0) {
;         unsigned* bar = b.bar;
;         __builtin_amdgcn_s_waitcnt(0);
;         unsigned nloc = b.st[0], nx = b.st[1];
;         if (nloc == 0u) { xcd_barrier_complete(bar, b.x, nloc, nx); b.st[0] = nloc; b.st[1] = nx; }
.Lt_skip:
	s_cmp_gt_i32 s79, 1
	s_cbranch_scc0 .LBB0_128
	s_waitcnt vmcnt(0)
	s_waitcnt lgkmcnt(0)
	s_barrier
	s_and_saveexec_b64 s[2:3], s[80:81]
	s_cbranch_execz .LBB0_127
	s_add_i32 s4, 0, 0x20020
	v_mov_b32_e32 v0, s4
	s_waitcnt vmcnt(0) expcnt(0) lgkmcnt(0)
	ds_read_b32 v2, v0
	s_add_i32 s4, 0, 0x20024
	v_mov_b32_e32 v0, s4
	ds_read_b32 v0, v0
	s_waitcnt lgkmcnt(1)
	v_cmp_ne_u32_e32 vcc, 0, v2
	s_cbranch_vccnz .LBB0_91
	v_readlane_b32 s4, v254, 0
	v_readlane_b32 s5, v254, 1
	s_load_dwordx2 s[12:13], s[4:5], 0x4
	s_add_u32 s4, s6, 0xff00200
	s_addc_u32 s5, s7, 0
	s_add_u32 s10, s6, 0xff00400
	s_addc_u32 s11, s7, 0
	s_waitcnt lgkmcnt(0)
	s_mul_i32 s48, s12, s33
	s_add_u32 s12, s6, 0xff00500
	s_mul_i32 s48, s48, s13
	s_addc_u32 s13, s7, 0
	s_add_u32 s14, s6, 0xff00600
	s_addc_u32 s15, s7, 0
	s_add_u32 s16, s6, 0xff00700
	s_addc_u32 s17, s7, 0
	s_add_u32 s18, s6, 0xff00800
	s_addc_u32 s19, s7, 0
	s_add_u32 s20, s6, 0xff00900
	s_addc_u32 s21, s7, 0
	s_add_u32 s22, s6, 0xff00a00
	s_addc_u32 s23, s7, 0
	s_add_u32 s24, s6, 0xff00b00
	s_addc_u32 s25, s7, 0
	s_add_u32 s26, s6, 0xff00c00
	s_addc_u32 s27, s7, 0
	s_add_u32 s28, s6, 0xff00d00
	s_addc_u32 s29, s7, 0
	s_add_u32 s30, s6, 0xff00e00
	s_addc_u32 s31, s7, 0
	s_add_u32 s34, s6, 0xff00f00
	s_addc_u32 s35, s7, 0
	s_add_u32 s36, s6, 0xff01000
	s_addc_u32 s37, s7, 0
	s_add_u32 s38, s6, 0xff01100
	s_addc_u32 s39, s7, 0
	s_add_u32 s40, s6, 0xff01200
	s_addc_u32 s41, s7, 0
	s_add_u32 s42, s6, 0xff01300
	s_addc_u32 s43, s7, 0
	s_mov_b32 s52, 1
	v_mov_b32_e32 v16, 0
	s_branch .LBB0_79
